# v17: P0 bias items (16 w1 loads hoisted, one wait) + rmsnorm fully unrolled with all 8 rows loaded up front
# baseline (speedup 1.0000x reference)
.LBB0_19:
	global_load_dwordx4 v[12:15], v[2:3], off offset:-2048 nt
	global_load_dwordx4 v[16:19], v[2:3], off offset:-1024 nt
	global_load_dwordx4 v[20:23], v[2:3], off nt
	global_load_dwordx4 v[24:27], v[2:3], off offset:1024 nt
	v_lshl_add_u64 v[2:3], v[2:3], 0, s[8:9]
	global_load_dwordx4 v[100:103], v[2:3], off offset:-2048 nt
	global_load_dwordx4 v[104:107], v[2:3], off offset:-1024 nt
	global_load_dwordx4 v[108:111], v[2:3], off nt
	global_load_dwordx4 v[112:115], v[2:3], off offset:1024 nt
	v_lshl_add_u64 v[2:3], v[2:3], 0, s[8:9]
	global_load_dwordx4 v[116:119], v[2:3], off offset:-2048 nt
	global_load_dwordx4 v[120:123], v[2:3], off offset:-1024 nt
	global_load_dwordx4 v[124:127], v[2:3], off nt
	global_load_dwordx4 v[128:131], v[2:3], off offset:1024 nt
	v_lshl_add_u64 v[2:3], v[2:3], 0, s[8:9]
	global_load_dwordx4 v[132:135], v[2:3], off offset:-2048 nt
	global_load_dwordx4 v[136:139], v[2:3], off offset:-1024 nt
	global_load_dwordx4 v[140:143], v[2:3], off nt
	global_load_dwordx4 v[144:147], v[2:3], off offset:1024 nt
	v_lshl_add_u64 v[2:3], v[2:3], 0, s[8:9]
	global_load_dwordx4 v[168:171], v[2:3], off offset:-2048 nt
	global_load_dwordx4 v[172:175], v[2:3], off offset:-1024 nt
	global_load_dwordx4 v[176:179], v[2:3], off nt
	global_load_dwordx4 v[180:183], v[2:3], off offset:1024 nt
	v_lshl_add_u64 v[2:3], v[2:3], 0, s[8:9]
	global_load_dwordx4 v[184:187], v[2:3], off offset:-2048 nt
	global_load_dwordx4 v[188:191], v[2:3], off offset:-1024 nt
	global_load_dwordx4 v[192:195], v[2:3], off nt
	global_load_dwordx4 v[196:199], v[2:3], off offset:1024 nt
	v_lshl_add_u64 v[2:3], v[2:3], 0, s[8:9]
	global_load_dwordx4 v[200:203], v[2:3], off offset:-2048 nt
	global_load_dwordx4 v[204:207], v[2:3], off offset:-1024 nt
	global_load_dwordx4 v[208:211], v[2:3], off nt
	global_load_dwordx4 v[212:215], v[2:3], off offset:1024 nt
	v_lshl_add_u64 v[2:3], v[2:3], 0, s[8:9]
	global_load_dwordx4 v[216:219], v[2:3], off offset:-2048 nt
	global_load_dwordx4 v[220:223], v[2:3], off offset:-1024 nt
	global_load_dwordx4 v[224:227], v[2:3], off nt
	global_load_dwordx4 v[228:231], v[2:3], off offset:1024 nt
	v_lshl_add_u64 v[2:3], v[2:3], 0, s[8:9]
	s_mov_b32 s0, 0x800000
	s_waitcnt vmcnt(28)
	v_add_u32_e32 v0, s6, v0
	v_mov_b32_e32 v234, v13
	v_mov_b32_e32 v235, v17
	v_mov_b32_e32 v232, v12
	v_mov_b32_e32 v233, v16
	v_pk_mul_f32 v[234:235], v[234:235], v[234:235]
	s_nop 0
	v_pk_fma_f32 v[232:233], v[232:233], v[232:233], v[234:235]
	v_mov_b32_e32 v234, v14
	v_mov_b32_e32 v235, v18
	v_pk_fma_f32 v[232:233], v[234:235], v[234:235], v[232:233]
	v_mov_b32_e32 v234, v15
	v_mov_b32_e32 v235, v19
	v_pk_fma_f32 v[236:237], v[234:235], v[234:235], v[232:233]
	s_nop 0
	v_add_f32_e32 v236, v236, v237
	v_mov_b32_e32 v240, v21
	v_mov_b32_e32 v241, v25
	v_mov_b32_e32 v238, v20
	v_mov_b32_e32 v239, v24
	v_pk_mul_f32 v[240:241], v[240:241], v[240:241]
	s_nop 0
	v_pk_fma_f32 v[238:239], v[238:239], v[238:239], v[240:241]
	v_mov_b32_e32 v240, v22
	v_mov_b32_e32 v241, v26
	v_pk_fma_f32 v[238:239], v[240:241], v[240:241], v[238:239]
	v_mov_b32_e32 v240, v23
	v_mov_b32_e32 v241, v27
	v_pk_fma_f32 v[238:239], v[240:241], v[240:241], v[238:239]
	s_nop 0
	v_add_f32_e32 v236, v236, v238
	v_add_f32_e32 v236, v236, v239
	ds_bpermute_b32 v237, v6, v236
	s_waitcnt lgkmcnt(0)
	v_add_f32_e32 v236, v236, v237
	ds_bpermute_b32 v237, v7, v236
	s_waitcnt lgkmcnt(0)
	v_add_f32_e32 v236, v236, v237
	ds_bpermute_b32 v237, v8, v236
	s_waitcnt lgkmcnt(0)
	v_add_f32_e32 v236, v236, v237
	ds_bpermute_b32 v237, v9, v236
	s_waitcnt lgkmcnt(0)
	v_add_f32_e32 v236, v236, v237
	ds_bpermute_b32 v237, v10, v236
	s_waitcnt lgkmcnt(0)
	v_add_f32_e32 v236, v236, v237
	ds_bpermute_b32 v237, v11, v236
	s_waitcnt lgkmcnt(0)
	v_add_f32_e32 v236, v236, v237
	v_fmamk_f32 v236, v236, 0x3a800000, v1
	v_cmp_gt_f32_e32 vcc, s0, v236
	v_mul_f32_e32 v237, 0x4b800000, v236
	s_nop 0
	v_cndmask_b32_e32 v236, v236, v237, vcc
	v_rsq_f32_e32 v236, v236
	s_nop 0
	v_mul_f32_e32 v237, 0x45800000, v236
	v_cndmask_b32_e32 v236, v236, v237, vcc
	v_pk_mul_f32 v[12:13], v[12:13], v[236:237] op_sel_hi:[1,0]
	v_pk_mul_f32 v[14:15], v[14:15], v[236:237] op_sel_hi:[1,0]
	v_cvt_pk_bf16_f32 v12, v12, v13
	v_cvt_pk_bf16_f32 v13, v14, v15
	global_store_dwordx2 v[4:5], v[12:13], off
	v_pk_mul_f32 v[16:17], v[16:17], v[236:237] op_sel_hi:[1,0]
	v_pk_mul_f32 v[18:19], v[18:19], v[236:237] op_sel_hi:[1,0]
	v_cvt_pk_bf16_f32 v16, v16, v17
	v_cvt_pk_bf16_f32 v17, v18, v19
	global_store_dwordx2 v[4:5], v[16:17], off offset:512
	v_pk_mul_f32 v[20:21], v[20:21], v[236:237] op_sel_hi:[1,0]
	v_pk_mul_f32 v[22:23], v[22:23], v[236:237] op_sel_hi:[1,0]
	v_cvt_pk_bf16_f32 v20, v20, v21
	v_cvt_pk_bf16_f32 v21, v22, v23
	global_store_dwordx2 v[4:5], v[20:21], off offset:1024
	v_pk_mul_f32 v[24:25], v[24:25], v[236:237] op_sel_hi:[1,0]
	v_pk_mul_f32 v[26:27], v[26:27], v[236:237] op_sel_hi:[1,0]
	v_cvt_pk_bf16_f32 v24, v24, v25
	v_cvt_pk_bf16_f32 v25, v26, v27
	global_store_dwordx2 v[4:5], v[24:25], off offset:1536
	v_lshl_add_u64 v[4:5], v[4:5], 0, s[10:11]
	s_waitcnt vmcnt(28)
	v_add_u32_e32 v0, s6, v0
	v_mov_b32_e32 v234, v101
	v_mov_b32_e32 v235, v105
	v_mov_b32_e32 v232, v100
	v_mov_b32_e32 v233, v104
	v_pk_mul_f32 v[234:235], v[234:235], v[234:235]
	s_nop 0
	v_pk_fma_f32 v[232:233], v[232:233], v[232:233], v[234:235]
	v_mov_b32_e32 v234, v102
	v_mov_b32_e32 v235, v106
	v_pk_fma_f32 v[232:233], v[234:235], v[234:235], v[232:233]
	v_mov_b32_e32 v234, v103
	v_mov_b32_e32 v235, v107
	v_pk_fma_f32 v[236:237], v[234:235], v[234:235], v[232:233]
	s_nop 0
	v_add_f32_e32 v236, v236, v237
	v_mov_b32_e32 v240, v109
	v_mov_b32_e32 v241, v113
	v_mov_b32_e32 v238, v108
	v_mov_b32_e32 v239, v112
	v_pk_mul_f32 v[240:241], v[240:241], v[240:241]
	s_nop 0
	v_pk_fma_f32 v[238:239], v[238:239], v[238:239], v[240:241]
	v_mov_b32_e32 v240, v110
	v_mov_b32_e32 v241, v114
	v_pk_fma_f32 v[238:239], v[240:241], v[240:241], v[238:239]
	v_mov_b32_e32 v240, v111
	v_mov_b32_e32 v241, v115
	v_pk_fma_f32 v[238:239], v[240:241], v[240:241], v[238:239]
	s_nop 0
	v_add_f32_e32 v236, v236, v238
	v_add_f32_e32 v236, v236, v239
	ds_bpermute_b32 v237, v6, v236
	s_waitcnt lgkmcnt(0)
	v_add_f32_e32 v236, v236, v237
	ds_bpermute_b32 v237, v7, v236
	s_waitcnt lgkmcnt(0)
	v_add_f32_e32 v236, v236, v237
	ds_bpermute_b32 v237, v8, v236
	s_waitcnt lgkmcnt(0)
	v_add_f32_e32 v236, v236, v237
	ds_bpermute_b32 v237, v9, v236
	s_waitcnt lgkmcnt(0)
	v_add_f32_e32 v236, v236, v237
	ds_bpermute_b32 v237, v10, v236
	s_waitcnt lgkmcnt(0)
	v_add_f32_e32 v236, v236, v237
	ds_bpermute_b32 v237, v11, v236
	s_waitcnt lgkmcnt(0)
	v_add_f32_e32 v236, v236, v237
	v_fmamk_f32 v236, v236, 0x3a800000, v1
	v_cmp_gt_f32_e32 vcc, s0, v236
	v_mul_f32_e32 v237, 0x4b800000, v236
	s_nop 0
	v_cndmask_b32_e32 v236, v236, v237, vcc
	v_rsq_f32_e32 v236, v236
	s_nop 0
	v_mul_f32_e32 v237, 0x45800000, v236
	v_cndmask_b32_e32 v236, v236, v237, vcc
	v_pk_mul_f32 v[100:101], v[100:101], v[236:237] op_sel_hi:[1,0]
	v_pk_mul_f32 v[102:103], v[102:103], v[236:237] op_sel_hi:[1,0]
	v_cvt_pk_bf16_f32 v100, v100, v101
	v_cvt_pk_bf16_f32 v101, v102, v103
	global_store_dwordx2 v[4:5], v[100:101], off
	v_pk_mul_f32 v[104:105], v[104:105], v[236:237] op_sel_hi:[1,0]
	v_pk_mul_f32 v[106:107], v[106:107], v[236:237] op_sel_hi:[1,0]
	v_cvt_pk_bf16_f32 v104, v104, v105
	v_cvt_pk_bf16_f32 v105, v106, v107
	global_store_dwordx2 v[4:5], v[104:105], off offset:512
	v_pk_mul_f32 v[108:109], v[108:109], v[236:237] op_sel_hi:[1,0]
	v_pk_mul_f32 v[110:111], v[110:111], v[236:237] op_sel_hi:[1,0]
	v_cvt_pk_bf16_f32 v108, v108, v109
	v_cvt_pk_bf16_f32 v109, v110, v111
	global_store_dwordx2 v[4:5], v[108:109], off offset:1024
	v_pk_mul_f32 v[112:113], v[112:113], v[236:237] op_sel_hi:[1,0]
	v_pk_mul_f32 v[114:115], v[114:115], v[236:237] op_sel_hi:[1,0]
	v_cvt_pk_bf16_f32 v112, v112, v113
	v_cvt_pk_bf16_f32 v113, v114, v115
	global_store_dwordx2 v[4:5], v[112:113], off offset:1536
	v_lshl_add_u64 v[4:5], v[4:5], 0, s[10:11]
	s_waitcnt vmcnt(28)
	v_add_u32_e32 v0, s6, v0
	v_mov_b32_e32 v234, v117
	v_mov_b32_e32 v235, v121
	v_mov_b32_e32 v232, v116
	v_mov_b32_e32 v233, v120
	v_pk_mul_f32 v[234:235], v[234:235], v[234:235]
	s_nop 0
	v_pk_fma_f32 v[232:233], v[232:233], v[232:233], v[234:235]
	v_mov_b32_e32 v234, v118
	v_mov_b32_e32 v235, v122
	v_pk_fma_f32 v[232:233], v[234:235], v[234:235], v[232:233]
	v_mov_b32_e32 v234, v119
	v_mov_b32_e32 v235, v123
	v_pk_fma_f32 v[236:237], v[234:235], v[234:235], v[232:233]
	s_nop 0
	v_add_f32_e32 v236, v236, v237
	v_mov_b32_e32 v240, v125
	v_mov_b32_e32 v241, v129
	v_mov_b32_e32 v238, v124
	v_mov_b32_e32 v239, v128
	v_pk_mul_f32 v[240:241], v[240:241], v[240:241]
	s_nop 0
	v_pk_fma_f32 v[238:239], v[238:239], v[238:239], v[240:241]
	v_mov_b32_e32 v240, v126
	v_mov_b32_e32 v241, v130
	v_pk_fma_f32 v[238:239], v[240:241], v[240:241], v[238:239]
	v_mov_b32_e32 v240, v127
	v_mov_b32_e32 v241, v131
	v_pk_fma_f32 v[238:239], v[240:241], v[240:241], v[238:239]
	s_nop 0
	v_add_f32_e32 v236, v236, v238
	v_add_f32_e32 v236, v236, v239
	ds_bpermute_b32 v237, v6, v236
	s_waitcnt lgkmcnt(0)
	v_add_f32_e32 v236, v236, v237
	ds_bpermute_b32 v237, v7, v236
	s_waitcnt lgkmcnt(0)
	v_add_f32_e32 v236, v236, v237
	ds_bpermute_b32 v237, v8, v236
	s_waitcnt lgkmcnt(0)
	v_add_f32_e32 v236, v236, v237
	ds_bpermute_b32 v237, v9, v236
	s_waitcnt lgkmcnt(0)
	v_add_f32_e32 v236, v236, v237
	ds_bpermute_b32 v237, v10, v236
	s_waitcnt lgkmcnt(0)
	v_add_f32_e32 v236, v236, v237
	ds_bpermute_b32 v237, v11, v236
	s_waitcnt lgkmcnt(0)
	v_add_f32_e32 v236, v236, v237
	v_fmamk_f32 v236, v236, 0x3a800000, v1
	v_cmp_gt_f32_e32 vcc, s0, v236
	v_mul_f32_e32 v237, 0x4b800000, v236
	s_nop 0
	v_cndmask_b32_e32 v236, v236, v237, vcc
	v_rsq_f32_e32 v236, v236
	s_nop 0
	v_mul_f32_e32 v237, 0x45800000, v236
	v_cndmask_b32_e32 v236, v236, v237, vcc
	v_pk_mul_f32 v[116:117], v[116:117], v[236:237] op_sel_hi:[1,0]
	v_pk_mul_f32 v[118:119], v[118:119], v[236:237] op_sel_hi:[1,0]
	v_cvt_pk_bf16_f32 v116, v116, v117
	v_cvt_pk_bf16_f32 v117, v118, v119
	global_store_dwordx2 v[4:5], v[116:117], off
	v_pk_mul_f32 v[120:121], v[120:121], v[236:237] op_sel_hi:[1,0]
	v_pk_mul_f32 v[122:123], v[122:123], v[236:237] op_sel_hi:[1,0]
	v_cvt_pk_bf16_f32 v120, v120, v121
	v_cvt_pk_bf16_f32 v121, v122, v123
	global_store_dwordx2 v[4:5], v[120:121], off offset:512
	v_pk_mul_f32 v[124:125], v[124:125], v[236:237] op_sel_hi:[1,0]
	v_pk_mul_f32 v[126:127], v[126:127], v[236:237] op_sel_hi:[1,0]
	v_cvt_pk_bf16_f32 v124, v124, v125
	v_cvt_pk_bf16_f32 v125, v126, v127
	global_store_dwordx2 v[4:5], v[124:125], off offset:1024
	v_pk_mul_f32 v[128:129], v[128:129], v[236:237] op_sel_hi:[1,0]
	v_pk_mul_f32 v[130:131], v[130:131], v[236:237] op_sel_hi:[1,0]
	v_cvt_pk_bf16_f32 v128, v128, v129
	v_cvt_pk_bf16_f32 v129, v130, v131
	global_store_dwordx2 v[4:5], v[128:129], off offset:1536
	v_lshl_add_u64 v[4:5], v[4:5], 0, s[10:11]
	s_waitcnt vmcnt(28)
	v_add_u32_e32 v0, s6, v0
	v_mov_b32_e32 v234, v133
	v_mov_b32_e32 v235, v137
	v_mov_b32_e32 v232, v132
	v_mov_b32_e32 v233, v136
	v_pk_mul_f32 v[234:235], v[234:235], v[234:235]
	s_nop 0
	v_pk_fma_f32 v[232:233], v[232:233], v[232:233], v[234:235]
	v_mov_b32_e32 v234, v134
	v_mov_b32_e32 v235, v138
	v_pk_fma_f32 v[232:233], v[234:235], v[234:235], v[232:233]
	v_mov_b32_e32 v234, v135
	v_mov_b32_e32 v235, v139
	v_pk_fma_f32 v[236:237], v[234:235], v[234:235], v[232:233]
	s_nop 0
	v_add_f32_e32 v236, v236, v237
	v_mov_b32_e32 v240, v141
	v_mov_b32_e32 v241, v145
	v_mov_b32_e32 v238, v140
	v_mov_b32_e32 v239, v144
	v_pk_mul_f32 v[240:241], v[240:241], v[240:241]
	s_nop 0
	v_pk_fma_f32 v[238:239], v[238:239], v[238:239], v[240:241]
	v_mov_b32_e32 v240, v142
	v_mov_b32_e32 v241, v146
	v_pk_fma_f32 v[238:239], v[240:241], v[240:241], v[238:239]
	v_mov_b32_e32 v240, v143
	v_mov_b32_e32 v241, v147
	v_pk_fma_f32 v[238:239], v[240:241], v[240:241], v[238:239]
	s_nop 0
	v_add_f32_e32 v236, v236, v238
	v_add_f32_e32 v236, v236, v239
	ds_bpermute_b32 v237, v6, v236
	s_waitcnt lgkmcnt(0)
	v_add_f32_e32 v236, v236, v237
	ds_bpermute_b32 v237, v7, v236
	s_waitcnt lgkmcnt(0)
	v_add_f32_e32 v236, v236, v237
	ds_bpermute_b32 v237, v8, v236
	s_waitcnt lgkmcnt(0)
	v_add_f32_e32 v236, v236, v237
	ds_bpermute_b32 v237, v9, v236
	s_waitcnt lgkmcnt(0)
	v_add_f32_e32 v236, v236, v237
	ds_bpermute_b32 v237, v10, v236
	s_waitcnt lgkmcnt(0)
	v_add_f32_e32 v236, v236, v237
	ds_bpermute_b32 v237, v11, v236
	s_waitcnt lgkmcnt(0)
	v_add_f32_e32 v236, v236, v237
	v_fmamk_f32 v236, v236, 0x3a800000, v1
	v_cmp_gt_f32_e32 vcc, s0, v236
	v_mul_f32_e32 v237, 0x4b800000, v236
	s_nop 0
	v_cndmask_b32_e32 v236, v236, v237, vcc
	v_rsq_f32_e32 v236, v236
	s_nop 0
	v_mul_f32_e32 v237, 0x45800000, v236
	v_cndmask_b32_e32 v236, v236, v237, vcc
	v_pk_mul_f32 v[132:133], v[132:133], v[236:237] op_sel_hi:[1,0]
	v_pk_mul_f32 v[134:135], v[134:135], v[236:237] op_sel_hi:[1,0]
	v_cvt_pk_bf16_f32 v132, v132, v133
	v_cvt_pk_bf16_f32 v133, v134, v135
	global_store_dwordx2 v[4:5], v[132:133], off
	v_pk_mul_f32 v[136:137], v[136:137], v[236:237] op_sel_hi:[1,0]
	v_pk_mul_f32 v[138:139], v[138:139], v[236:237] op_sel_hi:[1,0]
	v_cvt_pk_bf16_f32 v136, v136, v137
	v_cvt_pk_bf16_f32 v137, v138, v139
	global_store_dwordx2 v[4:5], v[136:137], off offset:512
	v_pk_mul_f32 v[140:141], v[140:141], v[236:237] op_sel_hi:[1,0]
	v_pk_mul_f32 v[142:143], v[142:143], v[236:237] op_sel_hi:[1,0]
	v_cvt_pk_bf16_f32 v140, v140, v141
	v_cvt_pk_bf16_f32 v141, v142, v143
	global_store_dwordx2 v[4:5], v[140:141], off offset:1024
	v_pk_mul_f32 v[144:145], v[144:145], v[236:237] op_sel_hi:[1,0]
	v_pk_mul_f32 v[146:147], v[146:147], v[236:237] op_sel_hi:[1,0]
	v_cvt_pk_bf16_f32 v144, v144, v145
	v_cvt_pk_bf16_f32 v145, v146, v147
	global_store_dwordx2 v[4:5], v[144:145], off offset:1536
	v_lshl_add_u64 v[4:5], v[4:5], 0, s[10:11]
	s_waitcnt vmcnt(28)
	v_add_u32_e32 v0, s6, v0
	v_mov_b32_e32 v234, v169
	v_mov_b32_e32 v235, v173
	v_mov_b32_e32 v232, v168
	v_mov_b32_e32 v233, v172
	v_pk_mul_f32 v[234:235], v[234:235], v[234:235]
	s_nop 0
	v_pk_fma_f32 v[232:233], v[232:233], v[232:233], v[234:235]
	v_mov_b32_e32 v234, v170
	v_mov_b32_e32 v235, v174
	v_pk_fma_f32 v[232:233], v[234:235], v[234:235], v[232:233]
	v_mov_b32_e32 v234, v171
	v_mov_b32_e32 v235, v175
	v_pk_fma_f32 v[236:237], v[234:235], v[234:235], v[232:233]
	s_nop 0
	v_add_f32_e32 v236, v236, v237
	v_mov_b32_e32 v240, v177
	v_mov_b32_e32 v241, v181
	v_mov_b32_e32 v238, v176
	v_mov_b32_e32 v239, v180
	v_pk_mul_f32 v[240:241], v[240:241], v[240:241]
	s_nop 0
	v_pk_fma_f32 v[238:239], v[238:239], v[238:239], v[240:241]
	v_mov_b32_e32 v240, v178
	v_mov_b32_e32 v241, v182
	v_pk_fma_f32 v[238:239], v[240:241], v[240:241], v[238:239]
	v_mov_b32_e32 v240, v179
	v_mov_b32_e32 v241, v183
	v_pk_fma_f32 v[238:239], v[240:241], v[240:241], v[238:239]
	s_nop 0
	v_add_f32_e32 v236, v236, v238
	v_add_f32_e32 v236, v236, v239
	ds_bpermute_b32 v237, v6, v236
	s_waitcnt lgkmcnt(0)
	v_add_f32_e32 v236, v236, v237
	ds_bpermute_b32 v237, v7, v236
	s_waitcnt lgkmcnt(0)
	v_add_f32_e32 v236, v236, v237
	ds_bpermute_b32 v237, v8, v236
	s_waitcnt lgkmcnt(0)
	v_add_f32_e32 v236, v236, v237
	ds_bpermute_b32 v237, v9, v236
	s_waitcnt lgkmcnt(0)
	v_add_f32_e32 v236, v236, v237
	ds_bpermute_b32 v237, v10, v236
	s_waitcnt lgkmcnt(0)
	v_add_f32_e32 v236, v236, v237
	ds_bpermute_b32 v237, v11, v236
	s_waitcnt lgkmcnt(0)
	v_add_f32_e32 v236, v236, v237
	v_fmamk_f32 v236, v236, 0x3a800000, v1
	v_cmp_gt_f32_e32 vcc, s0, v236
	v_mul_f32_e32 v237, 0x4b800000, v236
	s_nop 0
	v_cndmask_b32_e32 v236, v236, v237, vcc
	v_rsq_f32_e32 v236, v236
	s_nop 0
	v_mul_f32_e32 v237, 0x45800000, v236
	v_cndmask_b32_e32 v236, v236, v237, vcc
	v_pk_mul_f32 v[168:169], v[168:169], v[236:237] op_sel_hi:[1,0]
	v_pk_mul_f32 v[170:171], v[170:171], v[236:237] op_sel_hi:[1,0]
	v_cvt_pk_bf16_f32 v168, v168, v169
	v_cvt_pk_bf16_f32 v169, v170, v171
	global_store_dwordx2 v[4:5], v[168:169], off
	v_pk_mul_f32 v[172:173], v[172:173], v[236:237] op_sel_hi:[1,0]
	v_pk_mul_f32 v[174:175], v[174:175], v[236:237] op_sel_hi:[1,0]
	v_cvt_pk_bf16_f32 v172, v172, v173
	v_cvt_pk_bf16_f32 v173, v174, v175
	global_store_dwordx2 v[4:5], v[172:173], off offset:512
	v_pk_mul_f32 v[176:177], v[176:177], v[236:237] op_sel_hi:[1,0]
	v_pk_mul_f32 v[178:179], v[178:179], v[236:237] op_sel_hi:[1,0]
	v_cvt_pk_bf16_f32 v176, v176, v177
	v_cvt_pk_bf16_f32 v177, v178, v179
	global_store_dwordx2 v[4:5], v[176:177], off offset:1024
	v_pk_mul_f32 v[180:181], v[180:181], v[236:237] op_sel_hi:[1,0]
	v_pk_mul_f32 v[182:183], v[182:183], v[236:237] op_sel_hi:[1,0]
	v_cvt_pk_bf16_f32 v180, v180, v181
	v_cvt_pk_bf16_f32 v181, v182, v183
	global_store_dwordx2 v[4:5], v[180:181], off offset:1536
	v_lshl_add_u64 v[4:5], v[4:5], 0, s[10:11]
	s_waitcnt vmcnt(28)
	v_add_u32_e32 v0, s6, v0
	v_mov_b32_e32 v234, v185
	v_mov_b32_e32 v235, v189
	v_mov_b32_e32 v232, v184
	v_mov_b32_e32 v233, v188
	v_pk_mul_f32 v[234:235], v[234:235], v[234:235]
	s_nop 0
	v_pk_fma_f32 v[232:233], v[232:233], v[232:233], v[234:235]
	v_mov_b32_e32 v234, v186
	v_mov_b32_e32 v235, v190
	v_pk_fma_f32 v[232:233], v[234:235], v[234:235], v[232:233]
	v_mov_b32_e32 v234, v187
	v_mov_b32_e32 v235, v191
	v_pk_fma_f32 v[236:237], v[234:235], v[234:235], v[232:233]
	s_nop 0
	v_add_f32_e32 v236, v236, v237
	v_mov_b32_e32 v240, v193
	v_mov_b32_e32 v241, v197
	v_mov_b32_e32 v238, v192
	v_mov_b32_e32 v239, v196
	v_pk_mul_f32 v[240:241], v[240:241], v[240:241]
	s_nop 0
	v_pk_fma_f32 v[238:239], v[238:239], v[238:239], v[240:241]
	v_mov_b32_e32 v240, v194
	v_mov_b32_e32 v241, v198
	v_pk_fma_f32 v[238:239], v[240:241], v[240:241], v[238:239]
	v_mov_b32_e32 v240, v195
	v_mov_b32_e32 v241, v199
	v_pk_fma_f32 v[238:239], v[240:241], v[240:241], v[238:239]
	s_nop 0
	v_add_f32_e32 v236, v236, v238
	v_add_f32_e32 v236, v236, v239
	ds_bpermute_b32 v237, v6, v236
	s_waitcnt lgkmcnt(0)
	v_add_f32_e32 v236, v236, v237
	ds_bpermute_b32 v237, v7, v236
	s_waitcnt lgkmcnt(0)
	v_add_f32_e32 v236, v236, v237
	ds_bpermute_b32 v237, v8, v236
	s_waitcnt lgkmcnt(0)
	v_add_f32_e32 v236, v236, v237
	ds_bpermute_b32 v237, v9, v236
	s_waitcnt lgkmcnt(0)
	v_add_f32_e32 v236, v236, v237
	ds_bpermute_b32 v237, v10, v236
	s_waitcnt lgkmcnt(0)
	v_add_f32_e32 v236, v236, v237
	ds_bpermute_b32 v237, v11, v236
	s_waitcnt lgkmcnt(0)
	v_add_f32_e32 v236, v236, v237
	v_fmamk_f32 v236, v236, 0x3a800000, v1
	v_cmp_gt_f32_e32 vcc, s0, v236
	v_mul_f32_e32 v237, 0x4b800000, v236
	s_nop 0
	v_cndmask_b32_e32 v236, v236, v237, vcc
	v_rsq_f32_e32 v236, v236
	s_nop 0
	v_mul_f32_e32 v237, 0x45800000, v236
	v_cndmask_b32_e32 v236, v236, v237, vcc
	v_pk_mul_f32 v[184:185], v[184:185], v[236:237] op_sel_hi:[1,0]
	v_pk_mul_f32 v[186:187], v[186:187], v[236:237] op_sel_hi:[1,0]
	v_cvt_pk_bf16_f32 v184, v184, v185
	v_cvt_pk_bf16_f32 v185, v186, v187
	global_store_dwordx2 v[4:5], v[184:185], off
	v_pk_mul_f32 v[188:189], v[188:189], v[236:237] op_sel_hi:[1,0]
	v_pk_mul_f32 v[190:191], v[190:191], v[236:237] op_sel_hi:[1,0]
	v_cvt_pk_bf16_f32 v188, v188, v189
	v_cvt_pk_bf16_f32 v189, v190, v191
	global_store_dwordx2 v[4:5], v[188:189], off offset:512
	v_pk_mul_f32 v[192:193], v[192:193], v[236:237] op_sel_hi:[1,0]
	v_pk_mul_f32 v[194:195], v[194:195], v[236:237] op_sel_hi:[1,0]
	v_cvt_pk_bf16_f32 v192, v192, v193
	v_cvt_pk_bf16_f32 v193, v194, v195
	global_store_dwordx2 v[4:5], v[192:193], off offset:1024
	v_pk_mul_f32 v[196:197], v[196:197], v[236:237] op_sel_hi:[1,0]
	v_pk_mul_f32 v[198:199], v[198:199], v[236:237] op_sel_hi:[1,0]
	v_cvt_pk_bf16_f32 v196, v196, v197
	v_cvt_pk_bf16_f32 v197, v198, v199
	global_store_dwordx2 v[4:5], v[196:197], off offset:1536
	v_lshl_add_u64 v[4:5], v[4:5], 0, s[10:11]
	s_waitcnt vmcnt(28)
	v_add_u32_e32 v0, s6, v0
	v_mov_b32_e32 v234, v201
	v_mov_b32_e32 v235, v205
	v_mov_b32_e32 v232, v200
	v_mov_b32_e32 v233, v204
	v_pk_mul_f32 v[234:235], v[234:235], v[234:235]
	s_nop 0
	v_pk_fma_f32 v[232:233], v[232:233], v[232:233], v[234:235]
	v_mov_b32_e32 v234, v202
	v_mov_b32_e32 v235, v206
	v_pk_fma_f32 v[232:233], v[234:235], v[234:235], v[232:233]
	v_mov_b32_e32 v234, v203
	v_mov_b32_e32 v235, v207
	v_pk_fma_f32 v[236:237], v[234:235], v[234:235], v[232:233]
	s_nop 0
	v_add_f32_e32 v236, v236, v237
	v_mov_b32_e32 v240, v209
	v_mov_b32_e32 v241, v213
	v_mov_b32_e32 v238, v208
	v_mov_b32_e32 v239, v212
	v_pk_mul_f32 v[240:241], v[240:241], v[240:241]
	s_nop 0
	v_pk_fma_f32 v[238:239], v[238:239], v[238:239], v[240:241]
	v_mov_b32_e32 v240, v210
	v_mov_b32_e32 v241, v214
	v_pk_fma_f32 v[238:239], v[240:241], v[240:241], v[238:239]
	v_mov_b32_e32 v240, v211
	v_mov_b32_e32 v241, v215
	v_pk_fma_f32 v[238:239], v[240:241], v[240:241], v[238:239]
	s_nop 0
	v_add_f32_e32 v236, v236, v238
	v_add_f32_e32 v236, v236, v239
	ds_bpermute_b32 v237, v6, v236
	s_waitcnt lgkmcnt(0)
	v_add_f32_e32 v236, v236, v237
	ds_bpermute_b32 v237, v7, v236
	s_waitcnt lgkmcnt(0)
	v_add_f32_e32 v236, v236, v237
	ds_bpermute_b32 v237, v8, v236
	s_waitcnt lgkmcnt(0)
	v_add_f32_e32 v236, v236, v237
	ds_bpermute_b32 v237, v9, v236
	s_waitcnt lgkmcnt(0)
	v_add_f32_e32 v236, v236, v237
	ds_bpermute_b32 v237, v10, v236
	s_waitcnt lgkmcnt(0)
	v_add_f32_e32 v236, v236, v237
	ds_bpermute_b32 v237, v11, v236
	s_waitcnt lgkmcnt(0)
	v_add_f32_e32 v236, v236, v237
	v_fmamk_f32 v236, v236, 0x3a800000, v1
	v_cmp_gt_f32_e32 vcc, s0, v236
	v_mul_f32_e32 v237, 0x4b800000, v236
	s_nop 0
	v_cndmask_b32_e32 v236, v236, v237, vcc
	v_rsq_f32_e32 v236, v236
	s_nop 0
	v_mul_f32_e32 v237, 0x45800000, v236
	v_cndmask_b32_e32 v236, v236, v237, vcc
	v_pk_mul_f32 v[200:201], v[200:201], v[236:237] op_sel_hi:[1,0]
	v_pk_mul_f32 v[202:203], v[202:203], v[236:237] op_sel_hi:[1,0]
	v_cvt_pk_bf16_f32 v200, v200, v201
	v_cvt_pk_bf16_f32 v201, v202, v203
	global_store_dwordx2 v[4:5], v[200:201], off
	v_pk_mul_f32 v[204:205], v[204:205], v[236:237] op_sel_hi:[1,0]
	v_pk_mul_f32 v[206:207], v[206:207], v[236:237] op_sel_hi:[1,0]
	v_cvt_pk_bf16_f32 v204, v204, v205
	v_cvt_pk_bf16_f32 v205, v206, v207
	global_store_dwordx2 v[4:5], v[204:205], off offset:512
	v_pk_mul_f32 v[208:209], v[208:209], v[236:237] op_sel_hi:[1,0]
	v_pk_mul_f32 v[210:211], v[210:211], v[236:237] op_sel_hi:[1,0]
	v_cvt_pk_bf16_f32 v208, v208, v209
	v_cvt_pk_bf16_f32 v209, v210, v211
	global_store_dwordx2 v[4:5], v[208:209], off offset:1024
	v_pk_mul_f32 v[212:213], v[212:213], v[236:237] op_sel_hi:[1,0]
	v_pk_mul_f32 v[214:215], v[214:215], v[236:237] op_sel_hi:[1,0]
	v_cvt_pk_bf16_f32 v212, v212, v213
	v_cvt_pk_bf16_f32 v213, v214, v215
	global_store_dwordx2 v[4:5], v[212:213], off offset:1536
	v_lshl_add_u64 v[4:5], v[4:5], 0, s[10:11]
	s_waitcnt vmcnt(28)
	v_add_u32_e32 v0, s6, v0
	v_mov_b32_e32 v234, v217
	v_mov_b32_e32 v235, v221
	v_mov_b32_e32 v232, v216
	v_mov_b32_e32 v233, v220
	v_pk_mul_f32 v[234:235], v[234:235], v[234:235]
	s_nop 0
	v_pk_fma_f32 v[232:233], v[232:233], v[232:233], v[234:235]
	v_mov_b32_e32 v234, v218
	v_mov_b32_e32 v235, v222
	v_pk_fma_f32 v[232:233], v[234:235], v[234:235], v[232:233]
	v_mov_b32_e32 v234, v219
	v_mov_b32_e32 v235, v223
	v_pk_fma_f32 v[236:237], v[234:235], v[234:235], v[232:233]
	s_nop 0
	v_add_f32_e32 v236, v236, v237
	v_mov_b32_e32 v240, v225
	v_mov_b32_e32 v241, v229
	v_mov_b32_e32 v238, v224
	v_mov_b32_e32 v239, v228
	v_pk_mul_f32 v[240:241], v[240:241], v[240:241]
	s_nop 0
	v_pk_fma_f32 v[238:239], v[238:239], v[238:239], v[240:241]
	v_mov_b32_e32 v240, v226
	v_mov_b32_e32 v241, v230
	v_pk_fma_f32 v[238:239], v[240:241], v[240:241], v[238:239]
	v_mov_b32_e32 v240, v227
	v_mov_b32_e32 v241, v231
	v_pk_fma_f32 v[238:239], v[240:241], v[240:241], v[238:239]
	s_nop 0
	v_add_f32_e32 v236, v236, v238
	v_add_f32_e32 v236, v236, v239
	ds_bpermute_b32 v237, v6, v236
	s_waitcnt lgkmcnt(0)
	v_add_f32_e32 v236, v236, v237
	ds_bpermute_b32 v237, v7, v236
	s_waitcnt lgkmcnt(0)
	v_add_f32_e32 v236, v236, v237
	ds_bpermute_b32 v237, v8, v236
	s_waitcnt lgkmcnt(0)
	v_add_f32_e32 v236, v236, v237
	ds_bpermute_b32 v237, v9, v236
	s_waitcnt lgkmcnt(0)
	v_add_f32_e32 v236, v236, v237
	ds_bpermute_b32 v237, v10, v236
	s_waitcnt lgkmcnt(0)
	v_add_f32_e32 v236, v236, v237
	ds_bpermute_b32 v237, v11, v236
	s_waitcnt lgkmcnt(0)
	v_add_f32_e32 v236, v236, v237
	v_fmamk_f32 v236, v236, 0x3a800000, v1
	v_cmp_gt_f32_e32 vcc, s0, v236
	v_mul_f32_e32 v237, 0x4b800000, v236
	s_nop 0
	v_cndmask_b32_e32 v236, v236, v237, vcc
	v_rsq_f32_e32 v236, v236
	s_nop 0
	v_mul_f32_e32 v237, 0x45800000, v236
	v_cndmask_b32_e32 v236, v236, v237, vcc
	v_pk_mul_f32 v[216:217], v[216:217], v[236:237] op_sel_hi:[1,0]
	v_pk_mul_f32 v[218:219], v[218:219], v[236:237] op_sel_hi:[1,0]
	v_cvt_pk_bf16_f32 v216, v216, v217
	v_cvt_pk_bf16_f32 v217, v218, v219
	global_store_dwordx2 v[4:5], v[216:217], off
	v_pk_mul_f32 v[220:221], v[220:221], v[236:237] op_sel_hi:[1,0]
	v_pk_mul_f32 v[222:223], v[222:223], v[236:237] op_sel_hi:[1,0]
	v_cvt_pk_bf16_f32 v220, v220, v221
	v_cvt_pk_bf16_f32 v221, v222, v223
	global_store_dwordx2 v[4:5], v[220:221], off offset:512
	v_pk_mul_f32 v[224:225], v[224:225], v[236:237] op_sel_hi:[1,0]
	v_pk_mul_f32 v[226:227], v[226:227], v[236:237] op_sel_hi:[1,0]
	v_cvt_pk_bf16_f32 v224, v224, v225
	v_cvt_pk_bf16_f32 v225, v226, v227
	global_store_dwordx2 v[4:5], v[224:225], off offset:1024
	v_pk_mul_f32 v[228:229], v[228:229], v[236:237] op_sel_hi:[1,0]
	v_pk_mul_f32 v[230:231], v[230:231], v[236:237] op_sel_hi:[1,0]
	v_cvt_pk_bf16_f32 v228, v228, v229
	v_cvt_pk_bf16_f32 v229, v230, v231
	global_store_dwordx2 v[4:5], v[228:229], off offset:1536
	v_lshl_add_u64 v[4:5], v[4:5], 0, s[10:11]
	s_mov_b64 s[28:29], exec

.LBB0_43:
	global_load_dwordx4 v[0:3], v[6:7], off offset:-12
	global_load_dwordx4 v[10:13], v[6:7], off offset:-60
	global_load_dwordx4 v[80:83], v[6:7], off offset:-28
	global_load_dwordx4 v[84:87], v[6:7], off offset:-44
	s_movk_i32 s30, 0xd000
	v_add_co_u32_e32 v88, vcc, s30, v4
	s_nop 1
	v_addc_co_u32_e32 v89, vcc, -1, v5, vcc
	s_movk_i32 s30, 0xe000
	v_add_co_u32_e32 v90, vcc, s30, v4
	s_nop 1
	v_addc_co_u32_e32 v91, vcc, -1, v5, vcc
	s_movk_i32 s30, 0xf000
	v_add_co_u32_e32 v92, vcc, s30, v4
	s_nop 1
	v_addc_co_u32_e32 v93, vcc, -1, v5, vcc
	global_load_dword v100, v[88:89], off offset:-3072
	global_load_dword v101, v[88:89], off offset:-2048
	global_load_dword v102, v[88:89], off offset:-1024
	global_load_dword v104, v[90:91], off offset:-4096
	global_load_dword v105, v[90:91], off offset:-3072
	global_load_dword v106, v[90:91], off offset:-2048
	global_load_dword v107, v[90:91], off offset:-1024
	global_load_dword v108, v[90:91], off
	global_load_dword v109, v[92:93], off offset:-3072
	global_load_dword v110, v[92:93], off offset:-2048
	global_load_dword v111, v[92:93], off offset:-1024
	global_load_dword v112, v[4:5], off offset:-4096
	global_load_dword v113, v[4:5], off offset:-3072
	global_load_dword v114, v[4:5], off offset:-2048
	global_load_dword v115, v[4:5], off offset:-1024
	global_load_dword v116, v[4:5], off
	v_add_u32_e32 v8, -16, v8
	s_mov_b64 s[36:37], 0x4000
	v_lshl_add_u64 v[6:7], v[6:7], 0, 64
	v_lshl_add_u64 v[4:5], v[4:5], 0, s[36:37]
	v_cmp_eq_u32_e32 vcc, 0, v8
	s_or_b64 s[6:7], vcc, s[6:7]
	s_waitcnt vmcnt(0)
	v_mov_b32_e32 v14, v13
	v_mov_b32_e32 v15, v84
	v_mov_b32_e32 v84, v85
	v_mov_b32_e32 v85, v86
	v_mov_b32_e32 v86, v87
	v_mov_b32_e32 v87, v80
	v_mov_b32_e32 v80, v81
	v_mov_b32_e32 v81, v82
	v_mov_b32_e32 v82, v83
	v_mov_b32_e32 v83, v0
	v_mov_b32_e32 v0, v1
	v_mov_b32_e32 v1, v2
	v_fmac_f32_e32 v9, v10, v100
	v_fmac_f32_e32 v9, v11, v101
	v_fmac_f32_e32 v9, v12, v102
	v_pk_mul_f32 v[12:13], v[14:15], v[104:105]
	s_nop 0
	v_add_f32_e32 v2, v9, v12
	v_add_f32_e32 v2, v2, v13
	v_pk_mul_f32 v[12:13], v[84:85], v[106:107]
	s_nop 0
	v_add_f32_e32 v2, v2, v12
	v_add_f32_e32 v2, v2, v13
	v_pk_mul_f32 v[10:11], v[86:87], v[108:109]
	s_nop 0
	v_add_f32_e32 v2, v2, v10
	v_add_f32_e32 v2, v2, v11
	v_pk_mul_f32 v[10:11], v[80:81], v[110:111]
	s_nop 0
	v_add_f32_e32 v2, v2, v10
	v_add_f32_e32 v2, v2, v11
	v_pk_mul_f32 v[10:11], v[82:83], v[112:113]
	s_nop 0
	v_add_f32_e32 v2, v2, v10
	v_add_f32_e32 v2, v2, v11
	v_pk_mul_f32 v[0:1], v[0:1], v[114:115]
	s_nop 0
	v_add_f32_e32 v0, v2, v0
	v_add_f32_e32 v9, v0, v1
	v_fmac_f32_e32 v9, v3, v116
	s_andn2_b64 exec, exec, s[6:7]
	s_cbranch_execnz .LBB0_43
	s_or_b64 exec, exec, s[6:7]
	ds_write_b32 v60, v9
	s_waitcnt lgkmcnt(0)
	s_barrier
	s_and_saveexec_b64 s[6:7], s[8:9]
	s_cbranch_execz .LBB0_46
	ds_read2_b32 v[2:3], v60 offset1:4
	ds_read2_b32 v[4:5], v60 offset0:8 offset1:12
	s_lshl_b32 s30, s34, 2
	s_and_b32 s30, s30, 0xfc
	v_readlane_b32 s12, v255, 61
	s_waitcnt lgkmcnt(1)
	v_add_f32_e32 v2, 0, v2
	v_add_f32_e32 v2, v2, v3
	s_waitcnt lgkmcnt(0)
	v_add_f32_e32 v2, v2, v4
	v_add_f32_e32 v4, v2, v5
	ds_read2_b32 v[2:3], v60 offset0:16 offset1:20
	s_and_b64 s[10:11], s[10:11], exec
	v_readlane_b32 s24, v254, 9
	v_readlane_b32 s25, v254, 10
	v_readlane_b32 s26, v254, 11
	s_waitcnt lgkmcnt(0)
	v_add_f32_e32 v2, v4, v2
	v_add_f32_e32 v4, v2, v3
	ds_read2_b32 v[2:3], v60 offset0:24 offset1:28
	v_readlane_b32 s27, v254, 12
	s_cselect_b32 s10, s25, s27
	s_cselect_b32 s11, s24, s26
	v_mov_b32_e32 v0, s11
	s_waitcnt lgkmcnt(0)
	v_add_f32_e32 v2, v4, v2
	v_add_f32_e32 v4, v2, v3
	ds_read2_b32 v[2:3], v60 offset0:32 offset1:36
	v_mov_b32_e32 v1, s10
	v_or_b32_e32 v18, s30, v166
	v_lshl_add_u64 v[0:1], v[18:19], 2, v[0:1]
	v_readlane_b32 s13, v255, 62
	s_waitcnt lgkmcnt(0)
	v_add_f32_e32 v2, v4, v2
	v_add_f32_e32 v4, v2, v3
	ds_read2_b32 v[2:3], v60 offset0:40 offset1:44
	v_readlane_b32 s14, v255, 63
	v_readlane_b32 s15, v254, 0
	v_readlane_b32 s16, v254, 1
	v_readlane_b32 s17, v254, 2
	s_waitcnt lgkmcnt(0)
	v_add_f32_e32 v2, v4, v2
	v_add_f32_e32 v4, v2, v3
	ds_read2_b32 v[2:3], v60 offset0:48 offset1:52
	v_readlane_b32 s18, v254, 3
	v_readlane_b32 s19, v254, 4
	v_readlane_b32 s20, v254, 5
	v_readlane_b32 s21, v254, 6
	s_waitcnt lgkmcnt(0)
	v_add_f32_e32 v2, v4, v2
	v_add_f32_e32 v4, v2, v3
	ds_read2_b32 v[2:3], v60 offset0:56 offset1:60
	v_readlane_b32 s22, v254, 7
	v_readlane_b32 s23, v254, 8
	s_waitcnt lgkmcnt(0)
	v_add_f32_e32 v2, v4, v2
	v_add_f32_e32 v4, v2, v3
	ds_read2_b32 v[2:3], v60 offset0:64 offset1:68
	s_waitcnt lgkmcnt(0)
	v_add_f32_e32 v2, v4, v2
	v_add_f32_e32 v4, v2, v3
	ds_read2_b32 v[2:3], v60 offset0:72 offset1:76
	s_waitcnt lgkmcnt(0)
	v_add_f32_e32 v2, v4, v2
	v_add_f32_e32 v4, v2, v3
	ds_read2_b32 v[2:3], v60 offset0:80 offset1:84
	s_waitcnt lgkmcnt(0)
	v_add_f32_e32 v2, v4, v2
	v_add_f32_e32 v4, v2, v3
	ds_read2_b32 v[2:3], v60 offset0:88 offset1:92
	s_waitcnt lgkmcnt(0)
	v_add_f32_e32 v2, v4, v2
	v_add_f32_e32 v4, v2, v3
	ds_read2_b32 v[2:3], v60 offset0:96 offset1:100
	s_waitcnt lgkmcnt(0)
	v_add_f32_e32 v2, v4, v2
	v_add_f32_e32 v4, v2, v3
	ds_read2_b32 v[2:3], v60 offset0:104 offset1:108
	s_waitcnt lgkmcnt(0)
	v_add_f32_e32 v2, v4, v2
	v_add_f32_e32 v4, v2, v3
	ds_read2_b32 v[2:3], v60 offset0:112 offset1:116
	s_waitcnt lgkmcnt(0)
	v_add_f32_e32 v2, v4, v2
	v_add_f32_e32 v4, v2, v3
	ds_read2_b32 v[2:3], v60 offset0:120 offset1:124
	s_waitcnt lgkmcnt(0)
	v_add_f32_e32 v2, v4, v2
	v_add_f32_e32 v4, v2, v3
	ds_read2_b32 v[2:3], v60 offset0:128 offset1:132
	s_waitcnt lgkmcnt(0)
	v_add_f32_e32 v2, v4, v2
	v_add_f32_e32 v4, v2, v3
	ds_read2_b32 v[2:3], v60 offset0:136 offset1:140
	s_waitcnt lgkmcnt(0)
	v_add_f32_e32 v2, v4, v2
	v_add_f32_e32 v4, v2, v3
	ds_read2_b32 v[2:3], v60 offset0:144 offset1:148
	s_waitcnt lgkmcnt(0)
	v_add_f32_e32 v2, v4, v2
	v_add_f32_e32 v4, v2, v3
	ds_read2_b32 v[2:3], v60 offset0:152 offset1:156
	s_waitcnt lgkmcnt(0)
	v_add_f32_e32 v2, v4, v2
	v_add_f32_e32 v4, v2, v3
	ds_read2_b32 v[2:3], v60 offset0:160 offset1:164
	s_waitcnt lgkmcnt(0)
	v_add_f32_e32 v2, v4, v2
	v_add_f32_e32 v4, v2, v3
	ds_read2_b32 v[2:3], v60 offset0:168 offset1:172
	s_waitcnt lgkmcnt(0)
	v_add_f32_e32 v2, v4, v2
	v_add_f32_e32 v4, v2, v3
	ds_read2_b32 v[2:3], v60 offset0:176 offset1:180
	s_waitcnt lgkmcnt(0)
	v_add_f32_e32 v2, v4, v2
	v_add_f32_e32 v4, v2, v3
	ds_read2_b32 v[2:3], v60 offset0:184 offset1:188
	s_waitcnt lgkmcnt(0)
	v_add_f32_e32 v2, v4, v2
	v_add_f32_e32 v4, v2, v3
	ds_read2_b32 v[2:3], v60 offset0:192 offset1:196
	s_waitcnt lgkmcnt(0)
	v_add_f32_e32 v2, v4, v2
	v_add_f32_e32 v4, v2, v3
	ds_read2_b32 v[2:3], v60 offset0:200 offset1:204
	s_waitcnt lgkmcnt(0)
	v_add_f32_e32 v2, v4, v2
	v_add_f32_e32 v4, v2, v3
	ds_read2_b32 v[2:3], v60 offset0:208 offset1:212
	s_waitcnt lgkmcnt(0)
	v_add_f32_e32 v2, v4, v2
	v_add_f32_e32 v4, v2, v3
	ds_read2_b32 v[2:3], v60 offset0:216 offset1:220
	s_waitcnt lgkmcnt(0)
	v_add_f32_e32 v2, v4, v2
	v_add_f32_e32 v4, v2, v3
	ds_read2_b32 v[2:3], v60 offset0:224 offset1:228
	s_waitcnt lgkmcnt(0)
	v_add_f32_e32 v2, v4, v2
	v_add_f32_e32 v4, v2, v3
	ds_read2_b32 v[2:3], v60 offset0:232 offset1:236
	s_waitcnt lgkmcnt(0)
	v_add_f32_e32 v2, v4, v2
	v_add_f32_e32 v4, v2, v3
	ds_read2_b32 v[2:3], v60 offset0:240 offset1:244
	s_waitcnt lgkmcnt(0)
	v_add_f32_e32 v2, v4, v2
	v_add_f32_e32 v4, v2, v3
	ds_read2_b32 v[2:3], v60 offset0:248 offset1:252
	s_waitcnt lgkmcnt(0)
	v_add_f32_e32 v2, v4, v2
	v_add_f32_e32 v2, v2, v3
	global_store_dword v[0:1], v2, off
